# grid barrier: agent-scope L1 invalidate issued at arrival by an idle wave instead of by the polling wave after release
# speedup vs baseline: 1.0123x; 1.0123x over previous
; __device__ __forceinline__ void xcd_barrier(const XcdBarrier& b) {
;   asm volatile("s_waitcnt vmcnt(0)" ::: "memory");
;   __syncthreads();
;   if (threadIdx.x == 0) {
;     unsigned* bar = b.bar;
;     __builtin_amdgcn_s_waitcnt(0);
;     unsigned nloc = b.st[0], nx = b.st[1];
;     if (nloc == 0u) { xcd_barrier_complete(bar, b.x, nloc, nx); b.st[0] = nloc; b.st[1] = nx; }
.LBB0_1949:
	s_waitcnt vmcnt(0)
	s_waitcnt vmcnt(0) lgkmcnt(0)
	s_barrier
	v_readfirstlane_b32 s6, v168
	s_lshr_b32 s6, s6, 6
	s_cmp_eq_u32 s6, 1
	s_cbranch_scc0 .Leinv_skip
	buffer_inv sc1
	s_waitcnt vmcnt(0)
.Leinv_skip:
	s_mov_b64 s[6:7], exec
	v_readlane_b32 s8, v251, 2
	v_readlane_b32 s9, v251, 3
	s_and_b64 s[8:9], s[6:7], s[8:9]
	s_mov_b64 exec, s[8:9]
	s_cbranch_execnz .LBB0_1950
	s_getpc_b64 s[98:99]

; __device__ __forceinline__ unsigned xb_ld(unsigned* p)              { return __hip_atomic_load(p, __ATOMIC_RELAXED, __HIP_MEMORY_SCOPE_AGENT); }
; #define XB_SPIN(cond, bar) do { unsigned _sp = 0; while (cond) { __builtin_amdgcn_s_sleep(1); \
;     if ((++_sp & 255u) == 0u) { if (xb_ld(&(bar)[XB_TMO])) break; if (_sp > XB_SPIN_CAP) { atomicAdd(&(bar)[XB_TMO], 1u); break; } } } } while (0)
; __device__ __forceinline__ void xcd_barrier(const XcdBarrier& b) {
;     ...
;     } else {
;       XB_SPIN(xb_ld(&bar[XB_XGEN(b.x)]) == gen, bar);
;       __builtin_amdgcn_fence(__ATOMIC_ACQUIRE, "agent");
;       asm volatile("s_waitcnt vmcnt(0)" ::: "memory");
.LBB0_1980:
	s_or_b64 exec, exec, s[10:11]
	s_waitcnt vmcnt(0)
.LBB0_1981:
	s_andn2_saveexec_b64 s[8:9], s[8:9]
	s_cbranch_execnz .LBB0_1982
	s_getpc_b64 s[98:99]

; __device__ __forceinline__ unsigned xb_add(unsigned* p, unsigned v) { return __hip_atomic_fetch_add(p, v, __ATOMIC_RELAXED, __HIP_MEMORY_SCOPE_AGENT); }
; __device__ __forceinline__ void xcd_barrier(const XcdBarrier& b) {
;     ...
;       __builtin_amdgcn_fence(__ATOMIC_ACQUIRE, "agent");
;       xb_add(&bar[XB_XGEN(b.x)], 1u);
;       asm volatile("s_waitcnt vmcnt(0)" ::: "memory");
.LBB0_1998:
	s_or_b64 exec, exec, s[8:9]
	s_mov_b64 s[8:9], exec
	v_mbcnt_lo_u32_b32 v0, s8, 0
	v_mbcnt_hi_u32_b32 v0, s9, v0
	v_cmp_eq_u32_e32 vcc, 0, v0
	s_waitcnt vmcnt(0)
	s_and_saveexec_b64 s[10:11], vcc
	s_cbranch_execnz .LBB0_1999
	s_getpc_b64 s[98:99]
